# lever 4: attention B static s_setprio 1 for hw waves 4-7 per item, per-PV prio flips removed
# baseline (speedup 1.0000x reference)
; #define LAS __attribute__((address_space(3)))
; #define GAS __attribute__((address_space(1)))
; __device__ __forceinline__ unsigned cvt_pk_bf16(float lo, float hi) { unsigned r; asm volatile("v_cvt_pk_bf16_f32 %0, %1, %2" : "=v"(r) : "v"(lo), "v"(hi)); return r; }
; __device__ void attn_pair_block(LAS unsigned char* lds, const bf16_t* Qp, const bf16_t* Kp, const bf16_t* Vp, int qb, bf16_t* outp, const float negMB) {
;     ...
;     float lown = lrun + __shfl_xor(lrun, 32);
;     *(LAS float*)(xmine) = lown;
;     __syncthreads();
;     const float ltot = lown + *(const LAS float*)(xother);
;     const float inv = 1.0f / ltot;
; #pragma unroll
;     for (int d = 0; d < 4; ++d)
; #pragma unroll
;         for (int g = 0; g < 4; ++g) {
;             const int dd = stw * 128 + 32 * d + 8 * g + 4 * h;
;             u32x2 w; w.x = cvt_pk_bf16(o[d][4 * g] * inv, o[d][4 * g + 1] * inv); w.y = cvt_pk_bf16(o[d][4 * g + 2] * inv, o[d][4 * g + 3] * inv);
;             *(GAS u32x2*)(outp + (size_t)qpos * 2048 + dd) = w;
;         }
;     __syncthreads();
.LBB0_614:
	ds_bpermute_b32 v80, v184, v167
	v_add_u32_e32 v81, s13, v163
	s_waitcnt lgkmcnt(0)
	s_barrier
	s_waitcnt lgkmcnt(0)
	v_add_f32_e32 v80, v167, v80
	ds_write_b32 v81, v80
	s_waitcnt lgkmcnt(0)
	s_barrier
	ds_read_b32 v81, v88
	s_lshl_b32 s4, s11, 12
	s_add_u32 s6, s48, s4
	s_addc_u32 s7, s49, 0
	v_lshlrev_b32_e32 v154, 12, v156
	s_waitcnt lgkmcnt(0)
	v_add_f32_e32 v80, v80, v81
	v_div_scale_f32 v81, s[4:5], v80, v80, 1.0
	v_rcp_f32_e32 v82, v81
	s_lshl_b32 s4, s10, 9
	s_add_u32 s4, s6, s4
	s_addc_u32 s5, s7, 0
	v_fma_f32 v83, -v81, v82, 1.0
	v_fmac_f32_e32 v82, v83, v82
	v_div_scale_f32 v83, vcc, 1.0, v80, 1.0
	v_mul_f32_e32 v84, v83, v82
	v_fma_f32 v85, -v81, v84, v83
	v_fmac_f32_e32 v84, v85, v82
	v_fma_f32 v81, -v81, v84, v83
	v_div_fmas_f32 v81, v81, v82, v84
	v_div_fixup_f32 v84, v81, v80, 1.0
	v_lshl_or_b32 v80, s12, 7, v161
	v_mul_f32_e32 v64, v64, v84
	v_mul_f32_e32 v65, v65, v84
	v_lshl_add_u64 v[82:83], s[4:5], 0, v[154:155]
	v_cvt_pk_bf16_f32 v64, v64, v65
	v_mul_f32_e32 v65, v66, v84
	v_mul_f32_e32 v66, v67, v84
	v_ashrrev_i32_e32 v81, 31, v80
	v_cvt_pk_bf16_f32 v65, v65, v66
	v_lshl_add_u64 v[66:67], v[80:81], 1, v[82:83]
	global_store_dwordx2 v[66:67], v[64:65], off
	v_mul_f32_e32 v64, v68, v84
	v_mul_f32_e32 v65, v69, v84
	v_cvt_pk_bf16_f32 v64, v64, v65
	v_mul_f32_e32 v65, v70, v84
	v_mul_f32_e32 v68, v71, v84
	v_cvt_pk_bf16_f32 v65, v65, v68
	global_store_dwordx2 v[66:67], v[64:65], off offset:16
	v_mul_f32_e32 v64, v72, v84
	v_mul_f32_e32 v65, v73, v84
	v_cvt_pk_bf16_f32 v64, v64, v65
	v_mul_f32_e32 v65, v74, v84
	v_mul_f32_e32 v68, v75, v84
	v_cvt_pk_bf16_f32 v65, v65, v68
	global_store_dwordx2 v[66:67], v[64:65], off offset:32
	v_mul_f32_e32 v64, v76, v84
	v_mul_f32_e32 v65, v77, v84
	v_cvt_pk_bf16_f32 v64, v64, v65
	v_mul_f32_e32 v65, v78, v84
	v_mul_f32_e32 v48, v48, v84
	v_mul_f32_e32 v49, v49, v84
	v_mul_f32_e32 v68, v79, v84
	v_cvt_pk_bf16_f32 v65, v65, v68
	global_store_dwordx2 v[66:67], v[64:65], off offset:48
	v_cvt_pk_bf16_f32 v48, v48, v49
	v_mul_f32_e32 v49, v50, v84
	v_mul_f32_e32 v50, v51, v84
	v_cvt_pk_bf16_f32 v49, v49, v50
	global_store_dwordx2 v[66:67], v[48:49], off offset:64
	v_mul_f32_e32 v48, v52, v84
	v_mul_f32_e32 v49, v53, v84
	v_cvt_pk_bf16_f32 v48, v48, v49
	v_mul_f32_e32 v49, v54, v84
	v_mul_f32_e32 v50, v55, v84
	v_cvt_pk_bf16_f32 v49, v49, v50
	global_store_dwordx2 v[66:67], v[48:49], off offset:80
	v_mul_f32_e32 v48, v56, v84
	v_mul_f32_e32 v49, v57, v84
	v_cvt_pk_bf16_f32 v48, v48, v49
	v_mul_f32_e32 v49, v58, v84
	v_mul_f32_e32 v50, v59, v84
	v_cvt_pk_bf16_f32 v49, v49, v50
	global_store_dwordx2 v[66:67], v[48:49], off offset:96
	v_mul_f32_e32 v48, v60, v84
	v_mul_f32_e32 v49, v61, v84
	v_cvt_pk_bf16_f32 v48, v48, v49
	v_mul_f32_e32 v49, v62, v84
	v_mul_f32_e32 v32, v32, v84
	v_mul_f32_e32 v33, v33, v84
	v_mul_f32_e32 v50, v63, v84
	v_cvt_pk_bf16_f32 v49, v49, v50
	global_store_dwordx2 v[66:67], v[48:49], off offset:112
	v_cvt_pk_bf16_f32 v32, v32, v33
	v_mul_f32_e32 v33, v34, v84
	v_mul_f32_e32 v34, v35, v84
	v_cvt_pk_bf16_f32 v33, v33, v34
	global_store_dwordx2 v[66:67], v[32:33], off offset:128
	v_mul_f32_e32 v32, v36, v84
	v_mul_f32_e32 v33, v37, v84
	v_cvt_pk_bf16_f32 v32, v32, v33
	v_mul_f32_e32 v33, v38, v84
	v_mul_f32_e32 v34, v39, v84
	v_cvt_pk_bf16_f32 v33, v33, v34
	global_store_dwordx2 v[66:67], v[32:33], off offset:144
	v_mul_f32_e32 v32, v40, v84
	v_mul_f32_e32 v33, v41, v84
	v_cvt_pk_bf16_f32 v32, v32, v33
	v_mul_f32_e32 v33, v42, v84
	v_mul_f32_e32 v34, v43, v84
	v_cvt_pk_bf16_f32 v33, v33, v34
	global_store_dwordx2 v[66:67], v[32:33], off offset:160
	v_mul_f32_e32 v32, v44, v84
	v_mul_f32_e32 v33, v45, v84
	v_cvt_pk_bf16_f32 v32, v32, v33
	v_mul_f32_e32 v33, v46, v84
	v_mul_f32_e32 v16, v16, v84
	v_mul_f32_e32 v17, v17, v84
	v_mul_f32_e32 v34, v47, v84
	v_cvt_pk_bf16_f32 v33, v33, v34
	global_store_dwordx2 v[66:67], v[32:33], off offset:176
	v_cvt_pk_bf16_f32 v16, v16, v17
	v_mul_f32_e32 v17, v18, v84
	v_mul_f32_e32 v18, v19, v84
	v_cvt_pk_bf16_f32 v17, v17, v18
	global_store_dwordx2 v[66:67], v[16:17], off offset:192
	v_mul_f32_e32 v16, v20, v84
	v_mul_f32_e32 v17, v21, v84
	v_cvt_pk_bf16_f32 v16, v16, v17
	v_mul_f32_e32 v17, v22, v84
	v_mul_f32_e32 v18, v23, v84
	v_cvt_pk_bf16_f32 v17, v17, v18
	global_store_dwordx2 v[66:67], v[16:17], off offset:208
	v_mul_f32_e32 v16, v24, v84
	v_mul_f32_e32 v17, v25, v84
	v_cvt_pk_bf16_f32 v16, v16, v17
	v_mul_f32_e32 v17, v26, v84
	v_mul_f32_e32 v18, v27, v84
	v_cvt_pk_bf16_f32 v17, v17, v18
	global_store_dwordx2 v[66:67], v[16:17], off offset:224
	v_mul_f32_e32 v16, v28, v84
	v_mul_f32_e32 v17, v29, v84
	v_cvt_pk_bf16_f32 v16, v16, v17
	v_mul_f32_e32 v17, v30, v84
	v_mul_f32_e32 v18, v31, v84
	v_cvt_pk_bf16_f32 v17, v17, v18
	global_store_dwordx2 v[66:67], v[16:17], off offset:240
	s_setprio 0
	s_barrier

; #define GAS __attribute__((address_space(1)))
; __device__ __forceinline__ int opaque_tid() { int t = threadIdx.x; asm volatile("" : "+v"(t)); return t; }
; __device__ void attn_pair_block(LAS unsigned char* lds, const bf16_t* Qp, const bf16_t* Kp, const bf16_t* Vp, int qb, bf16_t* outp, const float negMB) {
;     const int tid = opaque_tid(), wid = __builtin_amdgcn_readfirstlane(tid >> 6), lane = tid & 63, c = lane & 31, h = lane >> 5;
;     const int stw = wid >> 2;
;     const int q0 = qb * 128 + (wid & 3) * 32, qpos = q0 + c;
;     bf16x8 qf[8];
; #pragma unroll
;     for (int ks = 0; ks < 8; ++ks) qf[ks] = *(const GAS bf16x8*)(Qp + (size_t)qpos * 1024 + ks * 16 + h * 8);
;     f32x16 o[4];
; #pragma unroll
;     for (int d = 0; d < 4; ++d)
; #pragma unroll
;         for (int r = 0; r < 16; ++r) o[d][r] = 0.f;
;     float lrun = 0.f;
;     const int nt = 2 * (qb + 1);
;     const int my_last = (q0 + 31) >> 6;
;     u32x4 kr[2], vr[4];
;     ...
;     PB_GLOAD(0); PB_LSTORE(0);
; __global__ void __launch_bounds__(512, 2) mega(Params p_unused) {
;     ...
;         const int qx = item >> 16, n = item & 0xFFFF;
;         if (n < 256) {
;             const int qb = 127 - (n >> 1), map = n & 1, b = qx & 1, hb = qx >> 1;
;             const size_t tok0 = (size_t)b * SEQ;
;             const bf16_t* Q = (const bf16_t*)(p.ws + WS_QB) + tok0 * 1024 + (hb * 2 + map) * 128;
;             const bf16_t* K = (const bf16_t*)(p.ws + WS_KB) + tok0 * 1024 + (hb * 2 + map) * 128;
;             const bf16_t* V = (const bf16_t*)(p.ws + WS_VB) + tok0 * 1024 + hb * 256;
;             bf16_t* O = (bf16_t*)(dout + DO_OB) + tok0 * 2048 + (hb * 2 + map) * 256;
;             attn_pair_block(lds, Q, K, V, qb, O, negMB_b);
.LBB0_803:
	s_and_b64 vcc, exec, s[4:5]
	s_cbranch_vccz .LBB0_615
	s_lshr_b32 s4, s83, 1
	s_lshr_b32 s6, s82, 17
	s_sub_i32 s16, 0x7f, s4
	s_and_b32 s8, s82, 1
	s_lshl_b32 s4, s84, 14
	s_lshl_b32 s5, s6, 1
	s_and_b32 s11, s4, 0x4000
	s_or_b32 s10, s5, s8
	s_lshl_b32 s4, s11, 11
	s_lshl_b32 s5, s10, 8
	s_add_u32 s7, s50, s4
	s_addc_u32 s9, s51, 0
	v_and_b32_e32 v50, 64, v214
	v_lshlrev_b32_e32 v50, 2, v50
	v_lshrrev_b32_e32 v51, 1, v214
	v_and_b32_e32 v51, 0xc0, v51
	v_or_b32_e32 v50, v50, v51
	v_and_b32_e32 v51, 63, v214
	v_or_b32_e32 v50, v50, v51
	s_add_u32 s4, s7, s5
	s_addc_u32 s5, s9, 0
	v_lshlrev_b32_e32 v28, 4, v50
	v_and_b32_e32 v40, 0xf0, v28
	v_mov_b32_e32 v41, v155
	v_ashrrev_i32_e32 v42, 4, v50
	v_add_u32_e32 v29, 0x200, v50
	s_lshl_b32 s23, s6, 9
	v_lshl_add_u64 v[16:17], s[4:5], 0, v[40:41]
	v_ashrrev_i32_e32 v43, 31, v42
	v_ashrrev_i32_e32 v160, 4, v29
	s_add_u32 s6, s7, s23
	v_lshl_add_u64 v[158:159], v[16:17], 0, s[58:59]
	v_lshlrev_b64 v[44:45], 11, v[42:43]
	v_ashrrev_i32_e32 v161, 31, v160
	s_addc_u32 s7, s9, 0
	s_add_u32 s100, s4, 0x1cc40000
	s_addc_u32 s101, s5, 0
	s_add_u32 s64, s6, 0x20c20000
	s_addc_u32 s65, s7, 0
	v_lshl_add_u64 v[24:25], v[158:159], 0, v[44:45]
	v_lshlrev_b64 v[16:17], 11, v[160:161]
	v_and_b32_e32 v162, 0x1f0, v28
	v_mov_b32_e32 v163, v155
	v_ashrrev_i32_e32 v166, 5, v50
	v_lshl_add_u64 v[26:27], v[158:159], 0, v[16:17]
	global_load_dwordx4 v[16:19], v[24:25], off
	global_load_dwordx4 v[20:23], v[26:27], off
	v_lshl_add_u64 v[24:25], s[6:7], 0, v[162:163]
	v_ashrrev_i32_e32 v167, 31, v166
	v_ashrrev_i32_e32 v168, 5, v29
	v_lshl_add_u64 v[164:165], v[24:25], 0, s[60:61]
	v_lshlrev_b64 v[24:25], 11, v[166:167]
	v_ashrrev_i32_e32 v169, 31, v168
	v_readfirstlane_b32 s6, v50
	v_lshl_add_u64 v[32:33], v[164:165], 0, v[24:25]
	v_lshlrev_b64 v[24:25], 11, v[168:169]
	s_ashr_i32 s7, s6, 6
	v_lshl_add_u64 v[34:35], v[164:165], 0, v[24:25]
	global_load_dwordx4 v[24:27], v[32:33], off
	global_load_dwordx4 v[28:31], v[34:35], off
	v_add_u32_e32 v32, 0x400, v50
	v_add_u32_e32 v36, 0x600, v50
	s_lshl_b32 s12, s7, 5
	v_ashrrev_i32_e32 v170, 5, v32
	v_ashrrev_i32_e32 v172, 5, v36
	v_lshl_add_u32 v250, v42, 11, v40
	v_lshl_add_u32 v251, v160, 11, v40
	v_lshl_add_u32 v246, v166, 11, v162
	v_lshl_add_u32 v247, v168, 11, v162
	v_lshl_add_u32 v248, v170, 11, v162
	v_lshl_add_u32 v249, v172, 11, v162
	s_lshl_b32 s9, s16, 7
	s_and_b32 s12, s12, 0x60
	v_ashrrev_i32_e32 v171, 31, v170
	v_ashrrev_i32_e32 v173, 31, v172
	v_and_b32_e32 v43, 31, v50
	s_or_b32 s18, s12, s9
	v_lshlrev_b64 v[32:33], 11, v[170:171]
	v_lshlrev_b64 v[36:37], 11, v[172:173]
	v_or_b32_e32 v156, s18, v43
	v_lshl_add_u64 v[32:33], v[164:165], 0, v[32:33]
	v_lshl_add_u64 v[36:37], v[164:165], 0, v[36:37]
	v_bfe_u32 v51, v50, 5, 1
	v_lshlrev_b32_e32 v154, 11, v156
	global_load_dwordx4 v[32:35], v[32:33], off
	v_lshl_add_u64 v[46:47], s[4:5], 0, v[154:155]
	global_load_dwordx4 v[36:39], v[36:37], off
	v_lshlrev_b32_e32 v154, 4, v51
	v_lshl_add_u64 v[46:47], v[46:47], 0, v[154:155]
	v_lshl_add_u64 v[48:49], v[46:47], 0, s[56:57]
	v_add_co_u32_e32 v46, vcc, s78, v46
	v_add_u32_e32 v185, 0, v40
	s_nop 0
	v_addc_co_u32_e32 v47, vcc, 0, v47, vcc
	global_load_dwordx4 v[120:123], v[48:49], off offset:32
	global_load_dwordx4 v[116:119], v[48:49], off offset:64
	global_load_dwordx4 v[112:115], v[48:49], off offset:96
	global_load_dwordx4 v[108:111], v[48:49], off offset:128
	global_load_dwordx4 v[100:103], v[48:49], off offset:160
	global_load_dwordx4 v[104:107], v[48:49], off offset:192
	global_load_dwordx4 v[124:127], v[46:47], off
	global_load_dwordx4 v[96:99], v[48:49], off offset:224
	v_mul_lo_u32 v186, v42, s79
	v_add_u32_e32 v40, v185, v186
	v_mul_lo_u32 v187, v160, s79
	v_mul_lo_u32 v188, v166, s80
	s_lshl_b32 s4, s7, 11
	s_ashr_i32 s12, s6, 8
	v_mul_lo_u32 v189, v168, s80
	s_add_i32 s13, s81, s4
	s_xor_b32 s4, s4, 0x2000
	v_mul_lo_u32 v190, v170, s80
	v_mul_lo_u32 v191, v172, s80
	s_lshr_b32 s21, s18, 6
	s_lshl_b32 s19, s12, 5
	s_and_b32 s14, s6, 0xffffff00
	s_add_i32 s15, s81, s4
	s_cmpk_lt_u32 s6, 0x100
	s_cselect_b64 s[6:7], -1, 0
	s_cmp_eq_u32 s12, 1
	v_lshlrev_b32_e32 v161, 2, v51
	s_cselect_b64 s[4:5], -1, 0
	s_and_b32 s9, s83, 0xfffe
	s_sub_i32 s22, 0xff, s9
	s_lshl_b32 s9, s82, 9
	s_lshl_b32 s8, s8, 8
	s_and_b32 s54, s9, 0x2000000
	s_or_b32 s8, s8, s23
	s_add_u32 s8, s50, s8
	s_addc_u32 s9, s51, 0
	v_and_b32_e32 v41, 63, v50
	v_lshlrev_b32_e32 v46, 3, v50
	v_and_b32_e32 v173, 24, v46
	v_lshlrev_b32_e32 v163, 4, v41
	s_mov_b32 s17, 63
	s_mov_b32 s20, 0
	v_sub_u32_e32 v183, v156, v161
	v_mov_b32_e32 v167, 0
	s_waitcnt vmcnt(13)
	ds_write_b128 v40, v[16:19]
	v_add_u32_e32 v16, v185, v187
	s_waitcnt vmcnt(12)
	ds_write_b128 v16, v[20:23]
	v_add_u32_e32 v16, 0, v162
	v_add_u32_e32 v17, v16, v188
	v_and_b32_e32 v18, 15, v50
	v_mov_b32_e32 v19, v155
	v_mov_b32_e32 v20, v155
	v_mov_b32_e32 v21, v155
	v_mov_b32_e32 v22, v155
	v_mov_b32_e32 v23, v155
	s_waitcnt vmcnt(11)
	ds_write_b128 v17, v[24:27] offset:17408
	v_add_u32_e32 v17, v16, v189
	s_waitcnt vmcnt(10)
	ds_write_b128 v17, v[28:31] offset:17408
	v_add_u32_e32 v17, v16, v190
	v_add_u32_e32 v16, v16, v191
	v_mov_b32_e32 v30, v155
	v_mov_b32_e32 v31, v155
	v_mov_b32_e32 v24, v155
	v_mov_b32_e32 v25, v155
	v_mov_b32_e32 v26, v155
	v_mov_b32_e32 v27, v155
	v_mov_b32_e32 v28, v155
	v_mov_b32_e32 v29, v155
	s_waitcnt vmcnt(9)
	ds_write_b128 v17, v[32:35] offset:17408
	s_waitcnt vmcnt(8)
	ds_write_b128 v16, v[36:39] offset:17408
	v_or_b32_e32 v16, s19, v43
	v_mul_lo_u32 v192, v16, s79
	v_lshrrev_b32_e32 v16, 2, v50
	v_and_or_b32 v16, v16, 3, v161
	v_mul_u32_u24_e32 v169, 0x240, v16
	v_lshlrev_b32_e32 v16, 1, v50
	v_and_b32_e32 v171, 32, v16
	v_lshl_add_u64 v[16:17], s[54:55], 0, v[44:45]
	v_lshl_or_b32 v16, v18, 4, v16
	v_lshl_add_u64 v[16:17], s[8:9], 0, v[16:17]
	v_lshl_add_u64 v[174:175], v[16:17], 0, s[62:63]
	v_mov_b32_e32 v16, v155
	v_mov_b32_e32 v17, v155
	v_mov_b32_e32 v18, v155
	v_mov_b64_e32 v[46:47], v[30:31]
	v_mov_b64_e32 v[62:63], v[30:31]
	v_mov_b64_e32 v[78:79], v[30:31]
	v_mov_b64_e32 v[44:45], v[28:29]
	v_mov_b64_e32 v[42:43], v[26:27]
	v_mov_b64_e32 v[40:41], v[24:25]
	v_mov_b64_e32 v[38:39], v[22:23]
	v_mov_b64_e32 v[36:37], v[20:21]
	v_mov_b64_e32 v[34:35], v[18:19]
	v_mov_b64_e32 v[32:33], v[16:17]
	v_mov_b64_e32 v[60:61], v[28:29]
	v_mov_b64_e32 v[58:59], v[26:27]
	v_mov_b64_e32 v[56:57], v[24:25]
	v_mov_b64_e32 v[54:55], v[22:23]
	v_mov_b64_e32 v[52:53], v[20:21]
	v_mov_b64_e32 v[50:51], v[18:19]
	v_mov_b64_e32 v[48:49], v[16:17]
	v_mov_b64_e32 v[76:77], v[28:29]
	v_mov_b64_e32 v[74:75], v[26:27]
	v_mov_b64_e32 v[72:73], v[24:25]
	v_mov_b64_e32 v[70:71], v[22:23]
	v_mov_b64_e32 v[68:69], v[20:21]
	v_mov_b64_e32 v[66:67], v[18:19]
	v_mov_b64_e32 v[64:65], v[16:17]
	v_add3_u32 v88, v160, s17, 1
	v_ashrrev_i32_e32 v89, 31, v88
	v_lshlrev_b64 v[88:89], 11, v[88:89]
	v_lshl_add_u64 v[88:89], v[158:159], 0, v[88:89]
	global_load_dwordx4 v[128:131], v[174:175], off
	global_load_dwordx4 v[136:139], v[88:89], off
	s_waitcnt vmcnt(2)
	s_waitcnt lgkmcnt(0)
	s_barrier
; #define LAS __attribute__((address_space(3)))
; __device__ void attn_pair_block(LAS unsigned char* lds, const bf16_t* Qp, const bf16_t* Kp, const bf16_t* Vp, int qb, bf16_t* outp, const float negMB) {
;     ...
;     for (int j = 0; j < nt; ++j) {
;         LAS unsigned char* kb = lds + (j & 1) * PSTAGE; LAS unsigned char* vb = kb + KBYTES;
;         if (j + 1 < nt) PB_GLOAD(j + 1);
;     ...
;         if (j + 1 < nt) PB_LSTORE((j + 1) & 1);
	v_readfirstlane_b32 s24, v214
	s_nop 1
	s_bitcmp1_b32 s24, 8
	s_cbranch_scc0 .Lpb_prio_done
	s_setprio 1
.Lpb_prio_done:
	s_branch .LBB0_806
.LBB0_805:
	s_add_i32 s20, s20, 1
	s_bitcmp1_b32 s20, 0
	s_cselect_b32 s8, 0xd400, 0
	s_add_i32 s23, s8, 0
	v_add_u32_e32 v88, s23, v162
	v_add_u32_e32 v89, v88, v188
	s_waitcnt vmcnt(5)
	ds_write_b128 v89, v[132:135] offset:17408
	v_add_u32_e32 v89, v88, v189
	s_waitcnt vmcnt(4)
	ds_write_b128 v89, v[144:147] offset:17408
	v_add_u32_e32 v89, v88, v190
	v_add_u32_e32 v88, v88, v191
	s_waitcnt vmcnt(3)
	ds_write_b128 v89, v[140:143] offset:17408
	s_waitcnt vmcnt(2)
	ds_write_b128 v88, v[148:151] offset:17408

; #define LAS __attribute__((address_space(3)))
; __device__ void attn_pair_block(LAS unsigned char* lds, const bf16_t* Qp, const bf16_t* Kp, const bf16_t* Vp, int qb, bf16_t* outp, const float negMB) {
;     ...
;         if (act) {
;             bf16x8 poth[2];
; #pragma unroll
;             for (int s2 = 0; s2 < 2; ++s2) poth[s2] = *(const LAS bf16x8*)(xother + s2 * 1024);
;             __builtin_amdgcn_s_setprio(1);
; #pragma unroll
;             for (int st = 0; st < 2; ++st)
; #pragma unroll
;                 for (int s2 = 0; s2 < 2; ++s2)
; #pragma unroll
;                     for (int d = 0; d < 4; ++d) {
;                         const s16x4 lo = __builtin_amdgcn_ds_read_tr16_b64_v4i16((LAS s16x4*)(vb + vread + (32 * st + 16 * s2) * VP2 + d * 64));
;                         const s16x4 hi = __builtin_amdgcn_ds_read_tr16_b64_v4i16((LAS s16x4*)(vb + vread + (32 * st + 16 * s2 + 8) * VP2 + d * 64));
;                         const bf16x8 vf = __builtin_shufflevector(lo, hi, 0, 1, 2, 3, 4, 5, 6, 7);
;                         const bf16x8 pfr = (st == stw) ? pown[s2] : poth[s2];
;                         o[d] = __builtin_amdgcn_mfma_f32_32x32x16_bf16(vf, pfr, o[d], 0, 0, 0);
;                     }
;             __builtin_amdgcn_sched_group_barrier(0x100, 8, 1);
; #pragma unroll
;             for (int i = 0; i < 16; ++i) { __builtin_amdgcn_sched_group_barrier(0x008, 1, 1); __builtin_amdgcn_sched_group_barrier(0x100, 2, 1); }
;             __builtin_amdgcn_s_setprio(0);
;         }
;         if (j + 1 < nt) PB_LSTORE((j + 1) & 1);
.LBB0_810:
	s_waitcnt lgkmcnt(0)
	s_barrier
	global_load_dwordx4 v[128:131], v250, s[100:101]
	global_load_dwordx4 v[136:139], v251, s[100:101]
	s_add_u32 s100, s100, 0x20000
	s_addc_u32 s101, s101, 0
	s_andn2_b64 vcc, exec, s[8:9]
	s_cbranch_vccnz .LBB0_805
	v_add_u32_e32 v92, s15, v163
	ds_read_b128 v[88:91], v92
	ds_read_b128 v[92:95], v92 offset:1024
	s_add_i32 s8, s14, s23
	s_mul_i32 s24, s12, 0x4800
	s_sub_i32 s25, 0x4800, s24
	v_add_u32_e32 v193, s8, v169
	v_add3_u32 v193, v193, v171, v173
	v_add_u32_e32 v194, s25, v193
	v_add_u32_e32 v193, s24, v193
	ds_read_b64_tr_b16 v[198:199], v193 offset:17408
	ds_read_b64_tr_b16 v[200:201], v193 offset:22016
	ds_read_b64_tr_b16 v[202:203], v193 offset:17472
	ds_read_b64_tr_b16 v[204:205], v193 offset:22080
	ds_read_b64_tr_b16 v[206:207], v193 offset:17536
	ds_read_b64_tr_b16 v[208:209], v193 offset:22144
	ds_read_b64_tr_b16 v[210:211], v193 offset:17600
	ds_read_b64_tr_b16 v[212:213], v193 offset:22208
	s_add_i32 s24, s20, 1
	s_bitcmp1_b32 s24, 0
	s_cselect_b32 s23, 0xd400, 0
	v_add_u32_e32 v242, s23, v162
	v_add_u32_e32 v243, v242, v188
	v_add_u32_e32 v244, v242, v189
	v_add_u32_e32 v245, v242, v190
	v_add_u32_e32 v242, v242, v191
	s_waitcnt lgkmcnt(6)
	v_mfma_f32_32x32x16_bf16 v[64:79], v[198:201], v[84:87], v[64:79]
	ds_read_b64_tr_b16 v[198:199], v193 offset:26624
	ds_read_b64_tr_b16 v[200:201], v193 offset:31232
	s_waitcnt lgkmcnt(6)
	v_mfma_f32_32x32x16_bf16 v[48:63], v[202:205], v[84:87], v[48:63]
	ds_read_b64_tr_b16 v[202:203], v193 offset:26688
	ds_read_b64_tr_b16 v[204:205], v193 offset:31296
	s_waitcnt lgkmcnt(6)
	v_mfma_f32_32x32x16_bf16 v[32:47], v[206:209], v[84:87], v[32:47]
	ds_read_b64_tr_b16 v[206:207], v193 offset:26752
	ds_read_b64_tr_b16 v[208:209], v193 offset:31360
	s_waitcnt vmcnt(5)
	ds_write_b128 v243, v[132:135] offset:17408
	s_waitcnt lgkmcnt(7)
	v_mfma_f32_32x32x16_bf16 v[16:31], v[210:213], v[84:87], v[16:31]
	ds_read_b64_tr_b16 v[210:211], v193 offset:26816
	ds_read_b64_tr_b16 v[212:213], v193 offset:31424
	s_waitcnt lgkmcnt(7)
	v_mfma_f32_32x32x16_bf16 v[64:79], v[198:201], v[80:83], v[64:79]
	ds_read_b64_tr_b16 v[198:199], v194 offset:17408
	ds_read_b64_tr_b16 v[200:201], v194 offset:22016
	s_waitcnt lgkmcnt(7)
	v_mfma_f32_32x32x16_bf16 v[48:63], v[202:205], v[80:83], v[48:63]
	ds_read_b64_tr_b16 v[202:203], v194 offset:17472
	ds_read_b64_tr_b16 v[204:205], v194 offset:22080
	s_waitcnt vmcnt(4)
	ds_write_b128 v244, v[144:147] offset:17408
	s_waitcnt lgkmcnt(8)
	v_mfma_f32_32x32x16_bf16 v[32:47], v[206:209], v[80:83], v[32:47]
	ds_read_b64_tr_b16 v[206:207], v194 offset:17536
	ds_read_b64_tr_b16 v[208:209], v194 offset:22144
	s_waitcnt lgkmcnt(7)
	v_mfma_f32_32x32x16_bf16 v[16:31], v[210:213], v[80:83], v[16:31]
	ds_read_b64_tr_b16 v[210:211], v194 offset:17600
	ds_read_b64_tr_b16 v[212:213], v194 offset:22208
	s_waitcnt lgkmcnt(7)
	v_mfma_f32_32x32x16_bf16 v[64:79], v[198:201], v[88:91], v[64:79]
	ds_read_b64_tr_b16 v[198:199], v194 offset:26624
	ds_read_b64_tr_b16 v[200:201], v194 offset:31232
	s_waitcnt vmcnt(3)
	ds_write_b128 v245, v[140:143] offset:17408
	s_waitcnt lgkmcnt(8)
	v_mfma_f32_32x32x16_bf16 v[48:63], v[202:205], v[88:91], v[48:63]
	ds_read_b64_tr_b16 v[202:203], v194 offset:26688
	ds_read_b64_tr_b16 v[204:205], v194 offset:31296
	s_waitcnt lgkmcnt(7)
	v_mfma_f32_32x32x16_bf16 v[32:47], v[206:209], v[88:91], v[32:47]
	ds_read_b64_tr_b16 v[206:207], v194 offset:26752
	ds_read_b64_tr_b16 v[208:209], v194 offset:31360
	s_waitcnt lgkmcnt(7)
	v_mfma_f32_32x32x16_bf16 v[16:31], v[210:213], v[88:91], v[16:31]
	ds_read_b64_tr_b16 v[210:211], v194 offset:26816
	ds_read_b64_tr_b16 v[212:213], v194 offset:31424
	s_waitcnt vmcnt(2)
	ds_write_b128 v242, v[148:151] offset:17408
	s_waitcnt lgkmcnt(8)
	v_mfma_f32_32x32x16_bf16 v[64:79], v[198:201], v[92:95], v[64:79]
	s_waitcnt lgkmcnt(5)
	v_mfma_f32_32x32x16_bf16 v[48:63], v[202:205], v[92:95], v[48:63]
	s_waitcnt lgkmcnt(3)
	v_mfma_f32_32x32x16_bf16 v[32:47], v[206:209], v[92:95], v[32:47]
	s_waitcnt lgkmcnt(1)
	v_mfma_f32_32x32x16_bf16 v[16:31], v[210:213], v[92:95], v[16:31]
	s_add_i32 s20, s20, 1
	s_branch .Lpb_tail

; #define LAS __attribute__((address_space(3)))
; __device__ void attn_pair_block(LAS unsigned char* lds, const bf16_t* Qp, const bf16_t* Kp, const bf16_t* Vp, int qb, bf16_t* outp, const float negMB) {
;     ...
;         if (act) {
;             bf16x8 poth[2];
; #pragma unroll
;             for (int s2 = 0; s2 < 2; ++s2) poth[s2] = *(const LAS bf16x8*)(xother + s2 * 1024);
;             __builtin_amdgcn_s_setprio(1);
; #pragma unroll
;             for (int st = 0; st < 2; ++st)
; #pragma unroll
;                 for (int s2 = 0; s2 < 2; ++s2)
; #pragma unroll
;                     for (int d = 0; d < 4; ++d) {
;                         const s16x4 lo = __builtin_amdgcn_ds_read_tr16_b64_v4i16((LAS s16x4*)(vb + vread + (32 * st + 16 * s2) * VP2 + d * 64));
;                         const s16x4 hi = __builtin_amdgcn_ds_read_tr16_b64_v4i16((LAS s16x4*)(vb + vread + (32 * st + 16 * s2 + 8) * VP2 + d * 64));
;                         const bf16x8 vf = __builtin_shufflevector(lo, hi, 0, 1, 2, 3, 4, 5, 6, 7);
;                         const bf16x8 pfr = (st == stw) ? pown[s2] : poth[s2];
;                         o[d] = __builtin_amdgcn_mfma_f32_32x32x16_bf16(vf, pfr, o[d], 0, 0, 0);
;                     }
;             __builtin_amdgcn_sched_group_barrier(0x100, 8, 1);
; #pragma unroll
;             for (int i = 0; i < 16; ++i) { __builtin_amdgcn_sched_group_barrier(0x008, 1, 1); __builtin_amdgcn_sched_group_barrier(0x100, 2, 1); }
;             __builtin_amdgcn_s_setprio(0);
;         }
.LBB0_816:
	s_waitcnt lgkmcnt(0)
	s_barrier
	s_andn2_b64 vcc, exec, s[8:9]
	v_add_u32_e32 v88, s15, v163
	s_cbranch_vccnz .LBB0_614
	ds_read_b128 v[90:93], v88
	ds_read_b128 v[94:97], v88 offset:1024
	s_add_i32 s14, s14, s23
	v_add_u32_e32 v89, s14, v169
	v_add3_u32 v89, v89, v171, v173
	ds_read_b64_tr_b16 v[102:103], v89 offset:17408
	ds_read_b64_tr_b16 v[104:105], v89 offset:22016
	ds_read_b64_tr_b16 v[106:107], v89 offset:17472
	ds_read_b64_tr_b16 v[108:109], v89 offset:22080
	ds_read_b64_tr_b16 v[110:111], v89 offset:17536
	ds_read_b64_tr_b16 v[112:113], v89 offset:22144
	ds_read_b64_tr_b16 v[114:115], v89 offset:17600
	ds_read_b64_tr_b16 v[116:117], v89 offset:22208
	s_waitcnt lgkmcnt(9)
	v_cndmask_b32_e64 v101, v93, v87, s[6:7]
	v_cndmask_b32_e64 v100, v92, v86, s[6:7]
	v_cndmask_b32_e64 v99, v91, v85, s[6:7]
	v_cndmask_b32_e64 v98, v90, v84, s[6:7]
	v_cndmask_b32_e64 v87, v93, v87, s[4:5]
	v_cndmask_b32_e64 v86, v92, v86, s[4:5]
	s_waitcnt lgkmcnt(6)
	v_mfma_f32_32x32x16_bf16 v[64:79], v[102:105], v[98:101], v[64:79]
	ds_read_b64_tr_b16 v[102:103], v89 offset:26624
	ds_read_b64_tr_b16 v[104:105], v89 offset:31232
	v_cndmask_b32_e64 v85, v91, v85, s[4:5]
	v_cndmask_b32_e64 v84, v90, v84, s[4:5]
	s_waitcnt lgkmcnt(6)
	v_mfma_f32_32x32x16_bf16 v[48:63], v[106:109], v[98:101], v[48:63]
	ds_read_b64_tr_b16 v[106:107], v89 offset:26688
	ds_read_b64_tr_b16 v[108:109], v89 offset:31296
	s_waitcnt lgkmcnt(6)
	v_mfma_f32_32x32x16_bf16 v[32:47], v[110:113], v[98:101], v[32:47]
	ds_read_b64_tr_b16 v[110:111], v89 offset:26752
	ds_read_b64_tr_b16 v[112:113], v89 offset:31360
	s_waitcnt lgkmcnt(6)
	v_mfma_f32_32x32x16_bf16 v[16:31], v[114:117], v[98:101], v[16:31]
	ds_read_b64_tr_b16 v[114:115], v89 offset:26816
	ds_read_b64_tr_b16 v[116:117], v89 offset:31424
	v_cndmask_b32_e64 v101, v97, v83, s[6:7]
	v_cndmask_b32_e64 v100, v96, v82, s[6:7]
	v_cndmask_b32_e64 v99, v95, v81, s[6:7]
	v_cndmask_b32_e64 v98, v94, v80, s[6:7]
	v_cndmask_b32_e64 v83, v97, v83, s[4:5]
	v_cndmask_b32_e64 v82, v96, v82, s[4:5]
	s_waitcnt lgkmcnt(6)
	v_mfma_f32_32x32x16_bf16 v[64:79], v[102:105], v[98:101], v[64:79]
	ds_read_b64_tr_b16 v[102:103], v89 offset:35840
	ds_read_b64_tr_b16 v[104:105], v89 offset:40448
	v_cndmask_b32_e64 v81, v95, v81, s[4:5]
	v_cndmask_b32_e64 v80, v94, v80, s[4:5]
	s_waitcnt lgkmcnt(6)
	v_mfma_f32_32x32x16_bf16 v[48:63], v[106:109], v[98:101], v[48:63]
	ds_read_b64_tr_b16 v[106:107], v89 offset:35904
	ds_read_b64_tr_b16 v[108:109], v89 offset:40512
	s_waitcnt lgkmcnt(6)
	v_mfma_f32_32x32x16_bf16 v[32:47], v[110:113], v[98:101], v[32:47]
	ds_read_b64_tr_b16 v[110:111], v89 offset:35968
	ds_read_b64_tr_b16 v[112:113], v89 offset:40576
	s_waitcnt lgkmcnt(6)
	v_mfma_f32_32x32x16_bf16 v[16:31], v[114:117], v[98:101], v[16:31]
	ds_read_b64_tr_b16 v[90:91], v89 offset:36032
	ds_read_b64_tr_b16 v[92:93], v89 offset:40640
	s_waitcnt lgkmcnt(6)
	v_mfma_f32_32x32x16_bf16 v[64:79], v[102:105], v[84:87], v[64:79]
	ds_read_b64_tr_b16 v[98:99], v89 offset:45056
	ds_read_b64_tr_b16 v[100:101], v89 offset:49664
	s_waitcnt lgkmcnt(6)
	v_mfma_f32_32x32x16_bf16 v[48:63], v[106:109], v[84:87], v[48:63]
	ds_read_b64_tr_b16 v[102:103], v89 offset:45120
	ds_read_b64_tr_b16 v[104:105], v89 offset:49728
	s_waitcnt lgkmcnt(6)
	v_mfma_f32_32x32x16_bf16 v[32:47], v[110:113], v[84:87], v[32:47]
	ds_read_b64_tr_b16 v[106:107], v89 offset:45184
	ds_read_b64_tr_b16 v[108:109], v89 offset:49792
	s_waitcnt lgkmcnt(6)
	v_mfma_f32_32x32x16_bf16 v[16:31], v[90:93], v[84:87], v[16:31]
	ds_read_b64_tr_b16 v[84:85], v89 offset:45248
	ds_read_b64_tr_b16 v[86:87], v89 offset:49856
	s_waitcnt lgkmcnt(6)
	v_mfma_f32_32x32x16_bf16 v[64:79], v[98:101], v[80:83], v[64:79]
	s_waitcnt lgkmcnt(4)
	v_mfma_f32_32x32x16_bf16 v[48:63], v[102:105], v[80:83], v[48:63]
	s_waitcnt lgkmcnt(2)
	v_mfma_f32_32x32x16_bf16 v[32:47], v[106:109], v[80:83], v[32:47]
	s_waitcnt lgkmcnt(0)
	v_mfma_f32_32x32x16_bf16 v[16:31], v[84:87], v[80:83], v[16:31]
	s_branch .LBB0_614
